# indexer scores phase: nt (streaming) hint on the f32 score stores (written once, read once by top-k)
# speedup vs baseline: 1.0018x; 1.0013x over previous
; DI f32x16 mfma32(bf16x8 a, bf16x8 b, f32x16 c) { return __builtin_amdgcn_mfma_f32_32x32x16_bf16(a, b, c, 0, 0, 0); }
; DI void idx_scores(const u16* kidx, const u16* qidx, const float* widx, float* scores) {
;     ...
; #pragma unroll 1
;     for (int hb4 = 0; hb4 < 2; ++hb4) {
;       bf16x8 qf[4][4];
;       const f32x4 w4 = *(const f32x4*)(widx + qrow * 8 + hb4 * 4);
; #pragma unroll
;       for (int h = 0; h < 4; ++h)
; #pragma unroll
;         for (int s = 0; s < 4; ++s) qf[h][s] = *(const bf16x8*)(qidx + qrow * 512 + (hb4 * 4 + h) * 64 + 16 * s + 8 * hh);
; #pragma unroll
;       for (int h = 0; h < 4; ++h) {
;         const float wh = w4[h];
; #pragma unroll
;         for (int kb = 0; kb < 2; ++kb) {
;           f32x16 S;
; #pragma unroll
;           for (int i = 0; i < 16; ++i) S[i] = 0.f;
; #pragma unroll
;           for (int s = 0; s < 4; ++s) S = mfma32(Kf[kb][s], qf[h][s], S);
; #pragma unroll
;           for (int i = 0; i < 16; ++i) acc[kb][i] += wh * fmaxf(S[i], 0.f);
;         }
;       }
.LBB0_804:
	v_cndmask_b32_e64 v0, 0, 1, s[20:21]
	s_lshl_b32 s2, s41, 2
	s_lshl_b32 s20, s41, 9
	v_cmp_ne_u32_e32 vcc, 1, v0
	v_lshl_add_u64 v[0:1], s[2:3], 2, v[156:157]
	s_mov_b32 s21, s3
	global_load_dwordx4 v[80:83], v[0:1], off
	v_lshl_add_u64 v[0:1], v[158:159], 0, s[20:21]
	global_load_dwordx4 v[132:135], v[0:1], off
	global_load_dwordx4 v[136:139], v[0:1], off offset:32
	global_load_dwordx4 v[140:143], v[0:1], off offset:64
	global_load_dwordx4 v[144:147], v[0:1], off offset:96
	global_load_dwordx4 v[116:119], v[0:1], off offset:128
	global_load_dwordx4 v[120:123], v[0:1], off offset:160
	global_load_dwordx4 v[124:127], v[0:1], off offset:192
	global_load_dwordx4 v[128:131], v[0:1], off offset:224
	global_load_dwordx4 v[100:103], v[0:1], off offset:256
	global_load_dwordx4 v[104:107], v[0:1], off offset:288
	global_load_dwordx4 v[108:111], v[0:1], off offset:320
	global_load_dwordx4 v[112:115], v[0:1], off offset:352
	global_load_dwordx4 v[96:99], v[0:1], off offset:384
	global_load_dwordx4 v[92:95], v[0:1], off offset:416
	global_load_dwordx4 v[84:87], v[0:1], off offset:448
	global_load_dwordx4 v[88:91], v[0:1], off offset:480
	s_mov_b32 s41, 1
	s_mov_b64 s[20:21], 0
	s_and_b64 vcc, exec, vcc
	s_waitcnt vmcnt(15)
	v_mfma_f32_32x32x16_bf16 v[0:15], v[48:51], v[132:135], 0
	s_waitcnt vmcnt(14)
	v_mfma_f32_32x32x16_bf16 v[0:15], v[52:55], v[136:139], v[0:15]
	s_waitcnt vmcnt(13)
	v_mfma_f32_32x32x16_bf16 v[0:15], v[56:59], v[140:143], v[0:15]
	s_waitcnt vmcnt(12)
	v_mfma_f32_32x32x16_bf16 v[0:15], v[60:63], v[144:147], v[0:15]
	s_nop 11
	v_max_f32_e32 v0, v0, v0
	v_max_f32_e32 v176, 0, v0
	v_max_f32_e32 v0, v1, v1
	v_max_f32_e32 v177, 0, v0
	v_max_f32_e32 v0, v2, v2
	v_max_f32_e32 v174, 0, v0
	v_max_f32_e32 v0, v3, v3
	v_max_f32_e32 v175, 0, v0
	v_max_f32_e32 v0, v4, v4
	v_max_f32_e32 v172, 0, v0
	v_max_f32_e32 v0, v5, v5
	v_max_f32_e32 v173, 0, v0
	v_max_f32_e32 v0, v6, v6
	v_max_f32_e32 v170, 0, v0
	v_max_f32_e32 v0, v7, v7
	v_max_f32_e32 v171, 0, v0
	v_max_f32_e32 v0, v8, v8
	v_max_f32_e32 v168, 0, v0
	v_max_f32_e32 v0, v9, v9
	v_max_f32_e32 v169, 0, v0
	v_max_f32_e32 v0, v10, v10
	v_max_f32_e32 v166, 0, v0
	v_max_f32_e32 v0, v11, v11
	v_max_f32_e32 v167, 0, v0
	v_max_f32_e32 v0, v12, v12
	v_max_f32_e32 v162, 0, v0
	v_max_f32_e32 v0, v13, v13
	v_max_f32_e32 v163, 0, v0
	v_max_f32_e32 v0, v14, v14
	v_max_f32_e32 v160, 0, v0
	v_max_f32_e32 v0, v15, v15
	v_max_f32_e32 v161, 0, v0
	v_mfma_f32_32x32x16_bf16 v[0:15], v[64:67], v[132:135], 0
	v_fma_f32 v44, v80, v176, v44
	v_fma_f32 v45, v80, v177, v45
	v_mov_b32_e32 v176, v83
	v_mfma_f32_32x32x16_bf16 v[0:15], v[68:71], v[136:139], v[0:15]
	v_mfma_f32_32x32x16_bf16 v[0:15], v[72:75], v[140:143], v[0:15]
	v_mfma_f32_32x32x16_bf16 v[0:15], v[76:79], v[144:147], v[0:15]
	s_nop 11
	v_max_f32_e32 v0, v0, v0
	v_max_f32_e32 v146, 0, v0
	v_max_f32_e32 v0, v1, v1
	v_max_f32_e32 v147, 0, v0
	v_max_f32_e32 v0, v2, v2
	v_max_f32_e32 v144, 0, v0
	v_max_f32_e32 v0, v3, v3
	v_max_f32_e32 v145, 0, v0
	v_max_f32_e32 v0, v4, v4
	v_max_f32_e32 v142, 0, v0
	v_max_f32_e32 v0, v5, v5
	v_max_f32_e32 v143, 0, v0
	v_max_f32_e32 v0, v6, v6
	v_max_f32_e32 v140, 0, v0
	v_max_f32_e32 v0, v7, v7
	v_max_f32_e32 v141, 0, v0
	v_max_f32_e32 v0, v8, v8
	v_max_f32_e32 v138, 0, v0
	v_max_f32_e32 v0, v9, v9
	v_max_f32_e32 v139, 0, v0
	v_max_f32_e32 v0, v10, v10
	v_max_f32_e32 v136, 0, v0
	v_max_f32_e32 v0, v11, v11
	v_max_f32_e32 v137, 0, v0
	v_max_f32_e32 v0, v12, v12
	v_max_f32_e32 v134, 0, v0
	v_max_f32_e32 v0, v13, v13
	v_max_f32_e32 v135, 0, v0
	v_max_f32_e32 v0, v14, v14
	v_max_f32_e32 v132, 0, v0
	v_max_f32_e32 v0, v15, v15
	v_max_f32_e32 v133, 0, v0
	s_waitcnt vmcnt(11)
	v_mfma_f32_32x32x16_bf16 v[0:15], v[48:51], v[116:119], 0
	v_fma_f32 v28, v80, v146, v28
	v_fma_f32 v29, v80, v147, v29
	s_waitcnt vmcnt(10)
	v_mfma_f32_32x32x16_bf16 v[0:15], v[52:55], v[120:123], v[0:15]
	s_waitcnt vmcnt(9)
	v_mfma_f32_32x32x16_bf16 v[0:15], v[56:59], v[124:127], v[0:15]
	s_waitcnt vmcnt(8)
	v_mfma_f32_32x32x16_bf16 v[0:15], v[60:63], v[128:131], v[0:15]
	s_nop 11
	v_max_f32_e32 v0, v0, v0
	v_max_f32_e32 v192, 0, v0
	v_max_f32_e32 v0, v1, v1
	v_max_f32_e32 v193, 0, v0
	v_max_f32_e32 v0, v2, v2
	v_max_f32_e32 v190, 0, v0
	v_max_f32_e32 v0, v3, v3
	v_max_f32_e32 v191, 0, v0
	v_max_f32_e32 v0, v4, v4
	v_max_f32_e32 v188, 0, v0
	v_max_f32_e32 v0, v5, v5
	v_max_f32_e32 v189, 0, v0
	v_max_f32_e32 v0, v6, v6
	v_max_f32_e32 v186, 0, v0
	v_max_f32_e32 v0, v7, v7
	v_max_f32_e32 v187, 0, v0
	v_max_f32_e32 v0, v8, v8
	v_max_f32_e32 v184, 0, v0
	v_max_f32_e32 v0, v9, v9
	v_max_f32_e32 v185, 0, v0
	v_max_f32_e32 v0, v10, v10
	v_max_f32_e32 v182, 0, v0
	v_max_f32_e32 v0, v11, v11
	v_max_f32_e32 v183, 0, v0
	v_max_f32_e32 v0, v12, v12
	v_max_f32_e32 v180, 0, v0
	v_max_f32_e32 v0, v13, v13
	v_max_f32_e32 v181, 0, v0
	v_max_f32_e32 v0, v14, v14
	v_max_f32_e32 v178, 0, v0
	v_max_f32_e32 v0, v15, v15
	v_max_f32_e32 v179, 0, v0
	v_mfma_f32_32x32x16_bf16 v[0:15], v[64:67], v[116:119], 0
	v_fma_f32 v44, v81, v192, v44
	v_fma_f32 v45, v81, v193, v45
	v_mfma_f32_32x32x16_bf16 v[0:15], v[68:71], v[120:123], v[0:15]
	v_mfma_f32_32x32x16_bf16 v[0:15], v[72:75], v[124:127], v[0:15]
	v_mfma_f32_32x32x16_bf16 v[0:15], v[76:79], v[128:131], v[0:15]
	s_nop 11
	v_max_f32_e32 v0, v0, v0
	v_max_f32_e32 v130, 0, v0
	v_max_f32_e32 v0, v1, v1
	v_max_f32_e32 v131, 0, v0
	v_max_f32_e32 v0, v2, v2
	v_max_f32_e32 v128, 0, v0
	v_max_f32_e32 v0, v3, v3
	v_max_f32_e32 v129, 0, v0
	v_max_f32_e32 v0, v4, v4
	v_max_f32_e32 v126, 0, v0
	v_max_f32_e32 v0, v5, v5
	v_max_f32_e32 v127, 0, v0
	v_max_f32_e32 v0, v6, v6
	v_max_f32_e32 v124, 0, v0
	v_max_f32_e32 v0, v7, v7
	v_max_f32_e32 v125, 0, v0
	v_max_f32_e32 v0, v8, v8
	v_max_f32_e32 v122, 0, v0
	v_max_f32_e32 v0, v9, v9
	v_max_f32_e32 v123, 0, v0
	v_max_f32_e32 v0, v10, v10
	v_max_f32_e32 v120, 0, v0
	v_max_f32_e32 v0, v11, v11
	v_max_f32_e32 v121, 0, v0
	v_max_f32_e32 v0, v12, v12
	v_max_f32_e32 v118, 0, v0
	v_max_f32_e32 v0, v13, v13
	v_max_f32_e32 v119, 0, v0
	v_max_f32_e32 v0, v14, v14
	v_max_f32_e32 v116, 0, v0
	v_max_f32_e32 v0, v15, v15
	v_max_f32_e32 v117, 0, v0
	s_waitcnt vmcnt(7)
; DI f32x16 mfma32(bf16x8 a, bf16x8 b, f32x16 c) { return __builtin_amdgcn_mfma_f32_32x32x16_bf16(a, b, c, 0, 0, 0); }
; DI void idx_scores(const u16* kidx, const u16* qidx, const float* widx, float* scores) {
;     ...
; #pragma unroll
;       for (int h = 0; h < 4; ++h) {
;         const float wh = w4[h];
; #pragma unroll
;         for (int kb = 0; kb < 2; ++kb) {
;           f32x16 S;
; #pragma unroll
;           for (int i = 0; i < 16; ++i) S[i] = 0.f;
; #pragma unroll
;           for (int s = 0; s < 4; ++s) S = mfma32(Kf[kb][s], qf[h][s], S);
; #pragma unroll
;           for (int i = 0; i < 16; ++i) acc[kb][i] += wh * fmaxf(S[i], 0.f);
;         }
;       }
	v_mfma_f32_32x32x16_bf16 v[0:15], v[48:51], v[100:103], 0
	v_fma_f32 v28, v81, v130, v28
	v_fma_f32 v29, v81, v131, v29
	s_waitcnt vmcnt(6)
	v_mfma_f32_32x32x16_bf16 v[0:15], v[52:55], v[104:107], v[0:15]
	s_waitcnt vmcnt(5)
	v_mfma_f32_32x32x16_bf16 v[0:15], v[56:59], v[108:111], v[0:15]
	s_waitcnt vmcnt(4)
	v_mfma_f32_32x32x16_bf16 v[0:15], v[60:63], v[112:115], v[0:15]
	s_nop 11
	v_max_f32_e32 v0, v0, v0
	v_max_f32_e32 v208, 0, v0
	v_max_f32_e32 v0, v1, v1
	v_max_f32_e32 v209, 0, v0
	v_max_f32_e32 v0, v2, v2
	v_max_f32_e32 v206, 0, v0
	v_max_f32_e32 v0, v3, v3
	v_max_f32_e32 v207, 0, v0
	v_max_f32_e32 v0, v4, v4
	v_max_f32_e32 v204, 0, v0
	v_max_f32_e32 v0, v5, v5
	v_max_f32_e32 v205, 0, v0
	v_max_f32_e32 v0, v6, v6
	v_max_f32_e32 v202, 0, v0
	v_max_f32_e32 v0, v7, v7
	v_max_f32_e32 v203, 0, v0
	v_max_f32_e32 v0, v8, v8
	v_max_f32_e32 v200, 0, v0
	v_max_f32_e32 v0, v9, v9
	v_max_f32_e32 v201, 0, v0
	v_max_f32_e32 v0, v10, v10
	v_max_f32_e32 v198, 0, v0
	v_max_f32_e32 v0, v11, v11
	v_max_f32_e32 v199, 0, v0
	v_max_f32_e32 v0, v12, v12
	v_max_f32_e32 v196, 0, v0
	v_max_f32_e32 v0, v13, v13
	v_max_f32_e32 v197, 0, v0
	v_max_f32_e32 v0, v14, v14
	v_max_f32_e32 v194, 0, v0
	v_max_f32_e32 v0, v15, v15
	v_max_f32_e32 v195, 0, v0
	v_mfma_f32_32x32x16_bf16 v[0:15], v[64:67], v[100:103], 0
	v_fma_f32 v44, v82, v208, v44
	v_fma_f32 v45, v82, v209, v45
	v_mfma_f32_32x32x16_bf16 v[0:15], v[68:71], v[104:107], v[0:15]
	v_mfma_f32_32x32x16_bf16 v[0:15], v[72:75], v[108:111], v[0:15]
	v_mfma_f32_32x32x16_bf16 v[0:15], v[76:79], v[112:115], v[0:15]
	s_nop 11
	v_max_f32_e32 v0, v0, v0
	v_max_f32_e32 v114, 0, v0
	v_max_f32_e32 v0, v1, v1
	v_max_f32_e32 v115, 0, v0
	v_max_f32_e32 v0, v2, v2
	v_max_f32_e32 v112, 0, v0
	v_max_f32_e32 v0, v3, v3
	v_max_f32_e32 v113, 0, v0
	v_max_f32_e32 v0, v4, v4
	v_max_f32_e32 v110, 0, v0
	v_max_f32_e32 v0, v5, v5
	v_max_f32_e32 v111, 0, v0
	v_max_f32_e32 v0, v6, v6
	v_max_f32_e32 v108, 0, v0
	v_max_f32_e32 v0, v7, v7
	v_max_f32_e32 v109, 0, v0
	v_max_f32_e32 v0, v8, v8
	v_max_f32_e32 v106, 0, v0
	v_max_f32_e32 v0, v9, v9
	v_max_f32_e32 v107, 0, v0
	v_max_f32_e32 v0, v10, v10
	v_max_f32_e32 v104, 0, v0
	v_max_f32_e32 v0, v11, v11
	v_max_f32_e32 v105, 0, v0
	v_max_f32_e32 v0, v12, v12
	v_max_f32_e32 v102, 0, v0
	v_max_f32_e32 v0, v13, v13
	v_max_f32_e32 v103, 0, v0
	v_max_f32_e32 v0, v14, v14
	v_max_f32_e32 v100, 0, v0
	v_max_f32_e32 v0, v15, v15
	v_max_f32_e32 v101, 0, v0
	s_waitcnt vmcnt(3)
	v_mfma_f32_32x32x16_bf16 v[0:15], v[48:51], v[96:99], 0
	v_fma_f32 v28, v82, v114, v28
	v_fma_f32 v29, v82, v115, v29
	s_waitcnt vmcnt(2)
	v_mfma_f32_32x32x16_bf16 v[0:15], v[52:55], v[92:95], v[0:15]
	s_waitcnt vmcnt(1)
	v_mfma_f32_32x32x16_bf16 v[0:15], v[56:59], v[84:87], v[0:15]
	s_waitcnt vmcnt(0)
; DI f32x16 mfma32(bf16x8 a, bf16x8 b, f32x16 c) { return __builtin_amdgcn_mfma_f32_32x32x16_bf16(a, b, c, 0, 0, 0); }
; DI void idx_scores(const u16* kidx, const u16* qidx, const float* widx, float* scores) {
;     ...
;       for (int h = 0; h < 4; ++h) {
;         const float wh = w4[h];
; #pragma unroll
;         for (int kb = 0; kb < 2; ++kb) {
;           f32x16 S;
; #pragma unroll
;           for (int i = 0; i < 16; ++i) S[i] = 0.f;
; #pragma unroll
;           for (int s = 0; s < 4; ++s) S = mfma32(Kf[kb][s], qf[h][s], S);
; #pragma unroll
;           for (int i = 0; i < 16; ++i) acc[kb][i] += wh * fmaxf(S[i], 0.f);
;         }
;       }
;     }
;     const bool rowok = qb == 0 ? (w == 0 && l31 < 16) : true;
;     if (rowok) {
; #pragma unroll
;       for (int kb = 0; kb < 2; ++kb)
; #pragma unroll
;         for (int g = 0; g < 4; ++g) {
;           const int kl = 32 * kb + 8 * g + 4 * hh;
;           if (kl + 3 < valid) {
;             f32x4 v = {acc[kb][4 * g], acc[kb][4 * g + 1], acc[kb][4 * g + 2], acc[kb][4 * g + 3]};
;             *(f32x4*)(scores + qrow * SROW + start + kl) = v;
;           }
;         }
	v_mfma_f32_32x32x16_bf16 v[0:15], v[60:63], v[88:91], v[0:15]
	s_nop 11
	v_max_f32_e32 v0, v0, v0
	v_max_f32_e32 v1, v1, v1
	v_max_f32_e32 v0, 0, v0
	v_max_f32_e32 v1, 0, v1
	v_pk_fma_f32 v[44:45], v[176:177], v[0:1], v[44:45] op_sel_hi:[0,1,1]
	v_max_f32_e32 v0, v2, v2
	v_max_f32_e32 v1, v3, v3
	v_pk_fma_f32 v[2:3], v[80:81], v[174:175], v[46:47] op_sel_hi:[0,1,1]
	v_pk_fma_f32 v[2:3], v[80:81], v[190:191], v[2:3] op_sel:[1,0,0]
	v_max_f32_e32 v0, 0, v0
	v_max_f32_e32 v1, 0, v1
	v_pk_fma_f32 v[2:3], v[82:83], v[206:207], v[2:3] op_sel_hi:[0,1,1]
	v_pk_fma_f32 v[46:47], v[176:177], v[0:1], v[2:3] op_sel_hi:[0,1,1]
	v_pk_fma_f32 v[2:3], v[80:81], v[172:173], v[40:41] op_sel_hi:[0,1,1]
	v_max_f32_e32 v0, v4, v4
	v_max_f32_e32 v1, v5, v5
	v_pk_fma_f32 v[2:3], v[80:81], v[188:189], v[2:3] op_sel:[1,0,0]
	v_max_f32_e32 v0, 0, v0
	v_max_f32_e32 v1, 0, v1
	v_pk_fma_f32 v[2:3], v[82:83], v[204:205], v[2:3] op_sel_hi:[0,1,1]
	v_pk_fma_f32 v[40:41], v[176:177], v[0:1], v[2:3] op_sel_hi:[0,1,1]
	v_pk_fma_f32 v[2:3], v[80:81], v[170:171], v[42:43] op_sel_hi:[0,1,1]
	v_max_f32_e32 v0, v6, v6
	v_max_f32_e32 v1, v7, v7
	v_pk_fma_f32 v[2:3], v[80:81], v[186:187], v[2:3] op_sel:[1,0,0]
	v_max_f32_e32 v0, 0, v0
	v_max_f32_e32 v1, 0, v1
	v_pk_fma_f32 v[2:3], v[82:83], v[202:203], v[2:3] op_sel_hi:[0,1,1]
	v_pk_fma_f32 v[42:43], v[176:177], v[0:1], v[2:3] op_sel_hi:[0,1,1]
	v_pk_fma_f32 v[2:3], v[80:81], v[168:169], v[36:37] op_sel_hi:[0,1,1]
	v_max_f32_e32 v0, v8, v8
	v_max_f32_e32 v1, v9, v9
	v_pk_fma_f32 v[2:3], v[80:81], v[184:185], v[2:3] op_sel:[1,0,0]
	v_max_f32_e32 v0, 0, v0
	v_max_f32_e32 v1, 0, v1
	v_pk_fma_f32 v[2:3], v[82:83], v[200:201], v[2:3] op_sel_hi:[0,1,1]
	v_pk_fma_f32 v[36:37], v[176:177], v[0:1], v[2:3] op_sel_hi:[0,1,1]
	v_pk_fma_f32 v[2:3], v[80:81], v[166:167], v[38:39] op_sel_hi:[0,1,1]
	v_max_f32_e32 v0, v10, v10
	v_max_f32_e32 v1, v11, v11
	v_pk_fma_f32 v[2:3], v[80:81], v[182:183], v[2:3] op_sel:[1,0,0]
	v_max_f32_e32 v0, 0, v0
	v_max_f32_e32 v1, 0, v1
	v_pk_fma_f32 v[2:3], v[82:83], v[198:199], v[2:3] op_sel_hi:[0,1,1]
	v_pk_fma_f32 v[38:39], v[176:177], v[0:1], v[2:3] op_sel_hi:[0,1,1]
	v_pk_fma_f32 v[2:3], v[80:81], v[162:163], v[32:33] op_sel_hi:[0,1,1]
	v_max_f32_e32 v0, v12, v12
	v_max_f32_e32 v1, v13, v13
	v_pk_fma_f32 v[2:3], v[80:81], v[180:181], v[2:3] op_sel:[1,0,0]
	v_max_f32_e32 v0, 0, v0
	v_max_f32_e32 v1, 0, v1
	v_pk_fma_f32 v[2:3], v[82:83], v[196:197], v[2:3] op_sel_hi:[0,1,1]
	v_pk_fma_f32 v[32:33], v[176:177], v[0:1], v[2:3] op_sel_hi:[0,1,1]
	v_pk_fma_f32 v[2:3], v[80:81], v[160:161], v[34:35] op_sel_hi:[0,1,1]
	v_max_f32_e32 v0, v14, v14
	v_max_f32_e32 v1, v15, v15
	v_pk_fma_f32 v[2:3], v[80:81], v[178:179], v[2:3] op_sel:[1,0,0]
	v_max_f32_e32 v0, 0, v0
	v_max_f32_e32 v1, 0, v1
	v_pk_fma_f32 v[2:3], v[82:83], v[194:195], v[2:3] op_sel_hi:[0,1,1]
	v_pk_fma_f32 v[34:35], v[176:177], v[0:1], v[2:3] op_sel_hi:[0,1,1]
	v_mfma_f32_32x32x16_bf16 v[0:15], v[64:67], v[96:99], 0
	v_mfma_f32_32x32x16_bf16 v[0:15], v[68:71], v[92:95], v[0:15]
	v_mfma_f32_32x32x16_bf16 v[0:15], v[72:75], v[84:87], v[0:15]
	v_mfma_f32_32x32x16_bf16 v[0:15], v[76:79], v[88:91], v[0:15]
	s_nop 11
	v_max_f32_e32 v0, v0, v0
	v_max_f32_e32 v1, v1, v1
	v_max_f32_e32 v0, 0, v0
	v_max_f32_e32 v1, 0, v1
	v_pk_fma_f32 v[28:29], v[176:177], v[0:1], v[28:29] op_sel_hi:[0,1,1]
	v_max_f32_e32 v0, v2, v2
	v_max_f32_e32 v1, v3, v3
	v_pk_fma_f32 v[2:3], v[80:81], v[144:145], v[30:31] op_sel_hi:[0,1,1]
	v_pk_fma_f32 v[2:3], v[80:81], v[128:129], v[2:3] op_sel:[1,0,0]
	v_max_f32_e32 v0, 0, v0
	v_max_f32_e32 v1, 0, v1
	v_pk_fma_f32 v[2:3], v[82:83], v[112:113], v[2:3] op_sel_hi:[0,1,1]
	v_pk_fma_f32 v[30:31], v[176:177], v[0:1], v[2:3] op_sel_hi:[0,1,1]
	v_pk_fma_f32 v[2:3], v[80:81], v[142:143], v[24:25] op_sel_hi:[0,1,1]
	v_max_f32_e32 v0, v4, v4
	v_max_f32_e32 v1, v5, v5
	v_pk_fma_f32 v[2:3], v[80:81], v[126:127], v[2:3] op_sel:[1,0,0]
	v_max_f32_e32 v0, 0, v0
	v_max_f32_e32 v1, 0, v1
	v_pk_fma_f32 v[2:3], v[82:83], v[110:111], v[2:3] op_sel_hi:[0,1,1]
	v_pk_fma_f32 v[24:25], v[176:177], v[0:1], v[2:3] op_sel_hi:[0,1,1]
	v_pk_fma_f32 v[2:3], v[80:81], v[140:141], v[26:27] op_sel_hi:[0,1,1]
	v_max_f32_e32 v0, v6, v6
	v_max_f32_e32 v1, v7, v7
	v_pk_fma_f32 v[2:3], v[80:81], v[124:125], v[2:3] op_sel:[1,0,0]
	v_max_f32_e32 v0, 0, v0
	v_max_f32_e32 v1, 0, v1
	v_pk_fma_f32 v[2:3], v[82:83], v[108:109], v[2:3] op_sel_hi:[0,1,1]
	v_pk_fma_f32 v[26:27], v[176:177], v[0:1], v[2:3] op_sel_hi:[0,1,1]
	v_pk_fma_f32 v[2:3], v[80:81], v[138:139], v[20:21] op_sel_hi:[0,1,1]
	v_max_f32_e32 v0, v8, v8
	v_max_f32_e32 v1, v9, v9
	v_pk_fma_f32 v[2:3], v[80:81], v[122:123], v[2:3] op_sel:[1,0,0]
	v_max_f32_e32 v0, 0, v0
	v_max_f32_e32 v1, 0, v1
	v_pk_fma_f32 v[2:3], v[82:83], v[106:107], v[2:3] op_sel_hi:[0,1,1]
	v_pk_fma_f32 v[20:21], v[176:177], v[0:1], v[2:3] op_sel_hi:[0,1,1]
	v_pk_fma_f32 v[2:3], v[80:81], v[136:137], v[22:23] op_sel_hi:[0,1,1]
	v_max_f32_e32 v0, v10, v10
	v_max_f32_e32 v1, v11, v11
	v_pk_fma_f32 v[2:3], v[80:81], v[120:121], v[2:3] op_sel:[1,0,0]
	v_max_f32_e32 v0, 0, v0
	v_max_f32_e32 v1, 0, v1
	v_pk_fma_f32 v[2:3], v[82:83], v[104:105], v[2:3] op_sel_hi:[0,1,1]
	v_pk_fma_f32 v[22:23], v[176:177], v[0:1], v[2:3] op_sel_hi:[0,1,1]
	v_pk_fma_f32 v[2:3], v[80:81], v[134:135], v[16:17] op_sel_hi:[0,1,1]
	v_max_f32_e32 v0, v12, v12
	v_max_f32_e32 v1, v13, v13
	v_pk_fma_f32 v[2:3], v[80:81], v[118:119], v[2:3] op_sel:[1,0,0]
	v_max_f32_e32 v0, 0, v0
	v_max_f32_e32 v1, 0, v1
	v_pk_fma_f32 v[2:3], v[82:83], v[102:103], v[2:3] op_sel_hi:[0,1,1]
	v_pk_fma_f32 v[16:17], v[176:177], v[0:1], v[2:3] op_sel_hi:[0,1,1]
	v_pk_fma_f32 v[2:3], v[80:81], v[132:133], v[18:19] op_sel_hi:[0,1,1]
	v_max_f32_e32 v0, v14, v14
	v_max_f32_e32 v1, v15, v15
	v_pk_fma_f32 v[2:3], v[80:81], v[116:117], v[2:3] op_sel:[1,0,0]
	v_max_f32_e32 v0, 0, v0
	v_max_f32_e32 v1, 0, v1
	v_pk_fma_f32 v[2:3], v[82:83], v[100:101], v[2:3] op_sel_hi:[0,1,1]
	v_pk_fma_f32 v[18:19], v[176:177], v[0:1], v[2:3] op_sel_hi:[0,1,1]
	s_cbranch_vccz .LBB0_804
	s_or_b64 s[20:21], s[6:7], s[4:5]
	s_and_saveexec_b64 s[6:7], s[20:21]
	s_cbranch_execz .LBB0_793
	s_and_b64 s[8:9], s[8:9], exec
	s_cselect_b32 s2, 16, 64
	s_lshl_b64 s[8:9], s[18:19], 2
	s_add_u32 s8, s24, s8
	s_addc_u32 s9, s25, s9
	v_mov_b64_e32 v[0:1], s[8:9]
	s_movk_i32 s14, 0x2080
	v_mad_u64_u32 v[0:1], s[8:9], v154, s14, v[0:1]
	v_mov_b32_e32 v2, v1
	v_mad_u64_u32 v[2:3], s[8:9], v155, s14, v[2:3]
	v_mov_b32_e32 v1, v2
	v_lshl_add_u64 v[0:1], v[0:1], 0, v[164:165]
	v_cmp_gt_u32_e32 vcc, s2, v221
	global_store_dwordx4 v[0:1], v[44:47], off nt
	global_store_dwordx4 v[0:1], v[40:43], off offset:32 nt
	s_and_saveexec_b64 s[8:9], vcc
	s_cbranch_execz .LBB0_812
	global_store_dwordx4 v[0:1], v[36:39], off offset:64 nt
	s_or_b64 exec, exec, s[8:9]
	v_cmp_gt_u32_e32 vcc, s2, v222
	s_and_saveexec_b64 s[8:9], vcc
	s_cbranch_execnz .LBB0_813

; DI void idx_scores(const u16* kidx, const u16* qidx, const float* widx, float* scores) {
;     ...
;     if (rowok) {
; #pragma unroll
;       for (int kb = 0; kb < 2; ++kb)
; #pragma unroll
;         for (int g = 0; g < 4; ++g) {
;           const int kl = 32 * kb + 8 * g + 4 * hh;
;           if (kl + 3 < valid) {
;             f32x4 v = {acc[kb][4 * g], acc[kb][4 * g + 1], acc[kb][4 * g + 2], acc[kb][4 * g + 3]};
;             *(f32x4*)(scores + qrow * SROW + start + kl) = v;
;           }
;         }
.LBB0_809:
	global_store_dwordx4 v[0:1], v[28:31], off offset:128 nt
	s_or_b64 exec, exec, s[8:9]
	v_cmp_gt_u32_e32 vcc, s2, v224
	s_and_saveexec_b64 s[8:9], vcc
	s_cbranch_execnz .LBB0_815

; DI void idx_scores(const u16* kidx, const u16* qidx, const float* widx, float* scores) {
;     ...
;     if (rowok) {
; #pragma unroll
;       for (int kb = 0; kb < 2; ++kb)
; #pragma unroll
;         for (int g = 0; g < 4; ++g) {
;           const int kl = 32 * kb + 8 * g + 4 * hh;
;           if (kl + 3 < valid) {
;             f32x4 v = {acc[kb][4 * g], acc[kb][4 * g + 1], acc[kb][4 * g + 2], acc[kb][4 * g + 3]};
;             *(f32x4*)(scores + qrow * SROW + start + kl) = v;
;           }
;         }
.LBB0_811:
	global_store_dwordx4 v[0:1], v[20:23], off offset:192 nt
	s_or_b64 exec, exec, s[8:9]
	v_cmp_gt_u32_e32 vcc, s2, v226
	s_and_b64 exec, exec, vcc
	s_cbranch_execz .LBB0_793
	s_branch .LBB0_817

; DI void idx_scores(const u16* kidx, const u16* qidx, const float* widx, float* scores) {
;     ...
;     if (rowok) {
; #pragma unroll
;       for (int kb = 0; kb < 2; ++kb)
; #pragma unroll
;         for (int g = 0; g < 4; ++g) {
;           const int kl = 32 * kb + 8 * g + 4 * hh;
;           if (kl + 3 < valid) {
;             f32x4 v = {acc[kb][4 * g], acc[kb][4 * g + 1], acc[kb][4 * g + 2], acc[kb][4 * g + 3]};
;             *(f32x4*)(scores + qrow * SROW + start + kl) = v;
;           }
;         }
.LBB0_813:
	global_store_dwordx4 v[0:1], v[32:35], off offset:96 nt
	s_or_b64 exec, exec, s[8:9]
	v_cmp_gt_u32_e32 vcc, s2, v223
	s_and_saveexec_b64 s[8:9], vcc
	s_cbranch_execnz .LBB0_809

; DI void idx_scores(const u16* kidx, const u16* qidx, const float* widx, float* scores) {
;     ...
;     if (rowok) {
; #pragma unroll
;       for (int kb = 0; kb < 2; ++kb)
; #pragma unroll
;         for (int g = 0; g < 4; ++g) {
;           const int kl = 32 * kb + 8 * g + 4 * hh;
;           if (kl + 3 < valid) {
;             f32x4 v = {acc[kb][4 * g], acc[kb][4 * g + 1], acc[kb][4 * g + 2], acc[kb][4 * g + 3]};
;             *(f32x4*)(scores + qrow * SROW + start + kl) = v;
;           }
;         }
.LBB0_815:
	global_store_dwordx4 v[0:1], v[24:27], off offset:160 nt
	s_or_b64 exec, exec, s[8:9]
	v_cmp_gt_u32_e32 vcc, s2, v225
	s_and_saveexec_b64 s[8:9], vcc
	s_cbranch_execnz .LBB0_811

; DI void idx_scores(const u16* kidx, const u16* qidx, const float* widx, float* scores) {
;     ...
;     if (rowok) {
; #pragma unroll
;       for (int kb = 0; kb < 2; ++kb)
; #pragma unroll
;         for (int g = 0; g < 4; ++g) {
;           const int kl = 32 * kb + 8 * g + 4 * hh;
;           if (kl + 3 < valid) {
;             f32x4 v = {acc[kb][4 * g], acc[kb][4 * g + 1], acc[kb][4 * g + 2], acc[kb][4 * g + 3]};
;             *(f32x4*)(scores + qrow * SROW + start + kl) = v;
;           }
;         }
.LBB0_817:
	global_store_dwordx4 v[0:1], v[16:19], off offset:224 nt
	s_branch .LBB0_793
